# grid barrier: non-leader workgroups wait on the cross-XCD release generation directly (one hop less); on top of v154
# baseline (speedup 1.0000x reference)
; __device__ __forceinline__ unsigned xb_ld(unsigned* p)              { return __hip_atomic_load(p, __ATOMIC_RELAXED, __HIP_MEMORY_SCOPE_AGENT); }
; __device__ __forceinline__ unsigned xb_add(unsigned* p, unsigned v) { return __hip_atomic_fetch_add(p, v, __ATOMIC_RELAXED, __HIP_MEMORY_SCOPE_AGENT); }
; #define XB_SPIN(cond, bar) do { unsigned _sp = 0; while (cond) { __builtin_amdgcn_s_sleep(1); \
;     if ((++_sp & 255u) == 0u) { if (xb_ld(&(bar)[XB_TMO])) break; if (_sp > XB_SPIN_CAP) { atomicAdd(&(bar)[XB_TMO], 1u); break; } } } } while (0)
; __device__ __forceinline__ void xcd_barrier(const XcdBarrier& b) {
;     ...
;         if (old + 1u == (gen + 1u) * nloc) {
;             __builtin_amdgcn_fence(__ATOMIC_RELEASE, "agent");
;             asm volatile("s_waitcnt vmcnt(0)" ::: "memory");
;             const unsigned og = xb_add(&bar[XB_TOP], 1u);
;             const unsigned tg = og / nx;
;             if (og + 1u == (tg + 1u) * nx) xb_add(&bar[XB_TOPGEN], 1u);
;             else XB_SPIN(xb_ld(&bar[XB_TOPGEN]) == tg, bar);
;             __builtin_amdgcn_fence(__ATOMIC_ACQUIRE, "agent");
;             xb_add(&bar[XB_XGEN(b.x)], 1u);
;             asm volatile("s_waitcnt vmcnt(0)" ::: "memory");
;         } else {
;             XB_SPIN(xb_ld(&bar[XB_XGEN(b.x)]) == gen, bar);
;             __builtin_amdgcn_fence(__ATOMIC_ACQUIRE, "agent");
;             asm volatile("s_waitcnt vmcnt(0)" ::: "memory");
.Lseam_nf0:
	v_add_u32_e32 v2, v4, v2
	v_cmp_ne_u32_e32 vcc, v3, v2
	s_and_saveexec_b64 s[4:5], vcc
	s_xor_b64 s[4:5], exec, s[4:5]
	s_cbranch_execz .LBB0_135
	s_waitcnt lgkmcnt(0)
	v_mov_b32_e32 v0, 0x70d7500
	global_load_dword v0, v0, s[74:75] sc1
	s_add_u32 s20, s74, 0x70d7500
	s_addc_u32 s21, s75, 0
	s_waitcnt vmcnt(0)
	v_cmp_eq_u32_e32 vcc, v0, v1
	s_and_saveexec_b64 s[6:7], vcc
	s_cbranch_execz .LBB0_134
	s_add_u32 s16, s74, 0x70d4200
	s_addc_u32 s17, s75, 0
	s_mov_b32 s15, 1
	s_mov_b64 s[22:23], 0
	v_mov_b32_e32 v0, 0
	s_branch .LBB0_125

; __device__ __forceinline__ unsigned xb_ld(unsigned* p)              { return __hip_atomic_load(p, __ATOMIC_RELAXED, __HIP_MEMORY_SCOPE_AGENT); }
; __device__ __forceinline__ unsigned xb_add(unsigned* p, unsigned v) { return __hip_atomic_fetch_add(p, v, __ATOMIC_RELAXED, __HIP_MEMORY_SCOPE_AGENT); }
; #define XB_SPIN(cond, bar) do { unsigned _sp = 0; while (cond) { __builtin_amdgcn_s_sleep(1); \
;     if ((++_sp & 255u) == 0u) { if (xb_ld(&(bar)[XB_TMO])) break; if (_sp > XB_SPIN_CAP) { atomicAdd(&(bar)[XB_TMO], 1u); break; } } } } while (0)
; __device__ __forceinline__ void xcd_barrier(const XcdBarrier& b) {
;     ...
;         if (old + 1u == (gen + 1u) * nloc) {
;             __builtin_amdgcn_fence(__ATOMIC_RELEASE, "agent");
;             asm volatile("s_waitcnt vmcnt(0)" ::: "memory");
;             const unsigned og = xb_add(&bar[XB_TOP], 1u);
;             const unsigned tg = og / nx;
;             if (og + 1u == (tg + 1u) * nx) xb_add(&bar[XB_TOPGEN], 1u);
;             else XB_SPIN(xb_ld(&bar[XB_TOPGEN]) == tg, bar);
;             __builtin_amdgcn_fence(__ATOMIC_ACQUIRE, "agent");
;             xb_add(&bar[XB_XGEN(b.x)], 1u);
;             asm volatile("s_waitcnt vmcnt(0)" ::: "memory");
;         } else {
;             XB_SPIN(xb_ld(&bar[XB_XGEN(b.x)]) == gen, bar);
;             __builtin_amdgcn_fence(__ATOMIC_ACQUIRE, "agent");
;             asm volatile("s_waitcnt vmcnt(0)" ::: "memory");
.Lseam_nf2:
	v_add_u32_e32 v2, v4, v2
	v_cmp_ne_u32_e32 vcc, v3, v2
	s_and_saveexec_b64 s[4:5], vcc
	s_xor_b64 s[4:5], exec, s[4:5]
	s_cbranch_execz .LBB0_349
	s_waitcnt lgkmcnt(0)
	v_mov_b32_e32 v0, 0x70d7500
	global_load_dword v0, v0, s[74:75] sc1
	s_add_u32 s10, s74, 0x70d7500
	s_addc_u32 s11, s75, 0
	s_waitcnt vmcnt(0)
	v_cmp_eq_u32_e32 vcc, v0, v1
	s_and_saveexec_b64 s[6:7], vcc
	s_cbranch_execz .LBB0_348
	s_add_u32 s8, s74, 0x70d4200
	s_addc_u32 s9, s75, 0
	s_mov_b32 s15, 1
	s_mov_b64 s[16:17], 0
	v_mov_b32_e32 v0, 0
	s_branch .LBB0_339

; __device__ __forceinline__ unsigned xb_ld(unsigned* p)              { return __hip_atomic_load(p, __ATOMIC_RELAXED, __HIP_MEMORY_SCOPE_AGENT); }
; __device__ __forceinline__ unsigned xb_add(unsigned* p, unsigned v) { return __hip_atomic_fetch_add(p, v, __ATOMIC_RELAXED, __HIP_MEMORY_SCOPE_AGENT); }
; #define XB_SPIN(cond, bar) do { unsigned _sp = 0; while (cond) { __builtin_amdgcn_s_sleep(1); \
;     if ((++_sp & 255u) == 0u) { if (xb_ld(&(bar)[XB_TMO])) break; if (_sp > XB_SPIN_CAP) { atomicAdd(&(bar)[XB_TMO], 1u); break; } } } } while (0)
; __device__ __forceinline__ void xcd_barrier(const XcdBarrier& b) {
;     ...
;         if (old + 1u == (gen + 1u) * nloc) {
;             __builtin_amdgcn_fence(__ATOMIC_RELEASE, "agent");
;             asm volatile("s_waitcnt vmcnt(0)" ::: "memory");
;             const unsigned og = xb_add(&bar[XB_TOP], 1u);
;             const unsigned tg = og / nx;
;             if (og + 1u == (tg + 1u) * nx) xb_add(&bar[XB_TOPGEN], 1u);
;             else XB_SPIN(xb_ld(&bar[XB_TOPGEN]) == tg, bar);
;             __builtin_amdgcn_fence(__ATOMIC_ACQUIRE, "agent");
;             xb_add(&bar[XB_XGEN(b.x)], 1u);
;             asm volatile("s_waitcnt vmcnt(0)" ::: "memory");
;         } else {
;             XB_SPIN(xb_ld(&bar[XB_XGEN(b.x)]) == gen, bar);
;             __builtin_amdgcn_fence(__ATOMIC_ACQUIRE, "agent");
;             asm volatile("s_waitcnt vmcnt(0)" ::: "memory");
.Lseam_nf9:
	v_add_u32_e32 v2, v4, v2
	v_cmp_ne_u32_e32 vcc, v3, v2
	s_and_saveexec_b64 s[4:5], vcc
	s_xor_b64 s[4:5], exec, s[4:5]
	s_cbranch_execz .LBB0_1048
	s_waitcnt lgkmcnt(0)
	v_mov_b32_e32 v0, 0x70d7500
	global_load_dword v0, v0, s[74:75] sc1
	s_add_u32 s10, s74, 0x70d7500
	s_addc_u32 s11, s75, 0
	s_waitcnt vmcnt(0)
	v_cmp_eq_u32_e32 vcc, v0, v1
	s_and_saveexec_b64 s[6:7], vcc
	s_cbranch_execz .LBB0_1047
	s_add_u32 s8, s74, 0x70d4200
	s_addc_u32 s9, s75, 0
	s_mov_b32 s15, 1
	s_mov_b64 s[12:13], 0
	v_mov_b32_e32 v0, 0
	s_branch .LBB0_1038
